# row-op parameter ladders de-serialised: all 20 parameter loads per run issued up front into free registers, one wait, then the products
# baseline (speedup 1.0000x reference)
; template <int MODE, bool FROM_IN>
; DI void rowop_run(const Params& p, int l, int row0, int nrows_run, int r, int lane, bool dry = false) {
;     constexpr bool HASY = MODE != 0;
;     const bool last = (MODE == 2 && l == 3);
;     f32x4 pa[4], pb[4], pc[4];
;     {
;         const float* ad = p.ada + ((size_t)l * 17 + r) * 6 * D;
;         int ln, so; const float* pre;
;         if (MODE == 0) { ln = 0; so = 0; pre = p.mix_pre_g; }
;         else if (MODE == 1) { ln = l; so = 3; pre = p.ffn_pre_g + l * D; }
;         else { ln = (l < 3) ? l + 1 : l; so = 0; pre = p.mix_pre_g + ((l < 3) ? l + 1 : l) * D; }
;         const float* ad2 = p.ada + ((size_t)ln * 17 + r) * 6 * D + so * D;
;         const float* gate = ad + (MODE == 1 ? 2 : 5) * D;
;         const float* pg = (MODE == 1 ? p.mix_post_g : p.ffn_post_g) + l * D;
; #pragma unroll
;         for (int i = 0; i < 4; ++i) {
;             const int c = (i * 64 + lane) * 4;
;             if (HASY) pa[i] = *(const f32x4*)(gate + c) * *(const f32x4*)(pg + c);
;             pb[i] = *(const f32x4*)(pre + c) * (*(const f32x4*)(ad2 + D + c) + 1.0f);
;             pc[i] = *(const f32x4*)(ad2 + c);
;         }
;     }
;     auto xptr = [&](int row) -> const float* { return row < NLAT ? p.x + (size_t)row * D : p.ctx + (size_t)(row - NLAT) * D; };
;     RowBuf cur, nxt;
;     rowop_load<HASY, FROM_IN>(cur, xptr(row0), p.xres + (size_t)row0 * D, p.Y + (size_t)row0 * D, lane);
.LBB0_122:
	v_ashrrev_i32_e32 v0, 7, v19
	v_readlane_b32 s0, v254, 28
	v_ashrrev_i32_e32 v1, 31, v0
	v_readlane_b32 s1, v254, 29
	v_mov_b64_e32 v[2:3], s[84:85]
	v_mov_b32_e32 v31, v129
	v_lshl_add_u64 v[0:1], s[0:1], 0, v[0:1]
	v_mad_u64_u32 v[2:3], s[0:1], v0, s3, v[2:3]
	v_mov_b32_e32 v0, v3
	v_mad_u64_u32 v[0:1], s[0:1], v1, s3, v[0:1]
	v_mov_b32_e32 v3, v0
	s_mov_b64 s[0:1], 0x3000
	v_lshl_add_u64 v[70:71], v[2:3], 0, s[0:1]
	s_mov_b64 s[0:1], 0x2000
	v_lshl_add_u64 v[60:61], v[2:3], 0, s[0:1]
	s_mov_b64 s[0:1], 0x4000
	v_lshl_add_u64 v[0:1], v[60:61], 0, v[128:129]
	v_lshl_add_u64 v[66:67], v[2:3], 0, s[0:1]
	global_load_dwordx4 v[152:155], v[0:1], off
	global_load_dwordx4 v[156:159], v[20:21], off
	v_mov_b32_e32 v33, v129
	v_mov_b32_e32 v35, v129
	v_lshlrev_b32_e32 v68, 5, v19
	v_ashrrev_i32_e32 v69, 31, v68
	v_lshlrev_b64 v[68:69], 11, v[68:69]
	s_mov_b32 s23, 0
	v_lshl_add_u64 v[4:5], v[66:67], 0, v[128:129]
	global_load_dwordx4 v[160:163], v[4:5], off
	global_load_dwordx4 v[164:167], v[22:23], off
	v_lshl_add_u64 v[0:1], v[70:71], 0, v[128:129]
	v_lshl_add_u64 v[4:5], v[60:61], 0, v[30:31]
	global_load_dwordx4 v[172:175], v[0:1], off
	global_load_dwordx4 v[176:179], v[4:5], off
	global_load_dwordx4 v[180:183], v[20:21], off offset:1024
	v_lshl_add_u64 v[8:9], v[66:67], 0, v[30:31]
	global_load_dwordx4 v[184:187], v[8:9], off
	global_load_dwordx4 v[188:191], v[22:23], off offset:1024
	v_lshl_add_u64 v[4:5], v[70:71], 0, v[30:31]
	v_lshl_add_u64 v[8:9], v[60:61], 0, v[32:33]
	global_load_dwordx4 v[192:195], v[4:5], off
	global_load_dwordx4 v[208:211], v[8:9], off
	global_load_dwordx4 v[212:215], v[20:21], off offset:2048
	v_lshl_add_u64 v[12:13], v[66:67], 0, v[32:33]
	global_load_dwordx4 v[216:219], v[12:13], off
	global_load_dwordx4 v[220:223], v[22:23], off offset:2048
	v_lshl_add_u64 v[8:9], v[70:71], 0, v[32:33]
	v_lshl_add_u64 v[12:13], v[60:61], 0, v[34:35]
	global_load_dwordx4 v[224:227], v[8:9], off
	global_load_dwordx4 v[228:231], v[12:13], off
	global_load_dwordx4 v[232:235], v[20:21], off offset:3072
	v_lshl_add_u64 v[64:65], v[66:67], 0, v[34:35]
	global_load_dwordx4 v[236:239], v[64:65], off
	global_load_dwordx4 v[240:243], v[22:23], off offset:3072
	v_lshl_add_u64 v[12:13], v[70:71], 0, v[34:35]
	v_lshl_add_u64 v[70:71], v[24:25], 0, v[68:69]
	v_lshl_add_u64 v[68:69], v[26:27], 0, v[68:69]
	global_load_dwordx4 v[244:247], v[12:13], off
	s_waitcnt vmcnt(0)
	v_pk_mul_f32 v[38:39], v[152:153], v[156:157]
	v_pk_mul_f32 v[36:37], v[154:155], v[158:159]
	v_pk_add_f32 v[4:5], v[160:161], 1.0 op_sel_hi:[1,0]
	v_pk_add_f32 v[6:7], v[162:163], 1.0 op_sel_hi:[1,0]
	v_pk_mul_f32 v[42:43], v[164:165], v[4:5]
	v_pk_mul_f32 v[40:41], v[166:167], v[6:7]
	v_pk_mul_f32 v[46:47], v[176:177], v[180:181]
	v_pk_mul_f32 v[44:45], v[178:179], v[182:183]
	v_pk_add_f32 v[8:9], v[184:185], 1.0 op_sel_hi:[1,0]
	v_pk_add_f32 v[10:11], v[186:187], 1.0 op_sel_hi:[1,0]
	v_pk_mul_f32 v[50:51], v[188:189], v[8:9]
	v_pk_mul_f32 v[48:49], v[190:191], v[10:11]
	v_pk_mul_f32 v[54:55], v[208:209], v[212:213]
	v_pk_mul_f32 v[52:53], v[210:211], v[214:215]
	v_pk_add_f32 v[12:13], v[216:217], 1.0 op_sel_hi:[1,0]
	v_pk_add_f32 v[14:15], v[218:219], 1.0 op_sel_hi:[1,0]
	v_pk_mul_f32 v[58:59], v[220:221], v[12:13]
	v_pk_mul_f32 v[56:57], v[222:223], v[14:15]
	v_pk_mul_f32 v[60:61], v[230:231], v[234:235]
	v_pk_mul_f32 v[62:63], v[228:229], v[232:233]
	v_pk_add_f32 v[66:67], v[238:239], 1.0 op_sel_hi:[1,0]
	v_pk_add_f32 v[72:73], v[236:237], 1.0 op_sel_hi:[1,0]
	v_pk_mul_f32 v[64:65], v[242:243], v[66:67]
	v_pk_mul_f32 v[66:67], v[240:241], v[72:73]
	v_mov_b64_e32 v[0:1], v[172:173]
	v_mov_b64_e32 v[2:3], v[174:175]
	v_mov_b64_e32 v[4:5], v[192:193]
	v_mov_b64_e32 v[6:7], v[194:195]
	v_mov_b64_e32 v[8:9], v[224:225]
	v_mov_b64_e32 v[10:11], v[226:227]
	v_mov_b64_e32 v[12:13], v[244:245]
	v_mov_b64_e32 v[14:15], v[246:247]
	global_load_dwordx2 v[92:93], v[70:71], off nt
	global_load_dwordx2 v[90:91], v[70:71], off offset:512 nt
	global_load_dwordx2 v[88:89], v[70:71], off offset:1024 nt
	global_load_dwordx2 v[84:85], v[70:71], off offset:1536 nt
	global_load_dwordx2 v[100:101], v[68:69], off nt
	global_load_dwordx2 v[98:99], v[68:69], off offset:512 nt
	global_load_dwordx2 v[94:95], v[68:69], off offset:1024 nt
	global_load_dwordx2 v[96:97], v[68:69], off offset:1536 nt
	s_waitcnt vmcnt(0)
	s_branch .LBB0_124

; template <int MODE, bool FROM_IN>
; DI void rowop_run(const Params& p, int l, int row0, int nrows_run, int r, int lane, bool dry = false) {
;     constexpr bool HASY = MODE != 0;
;     const bool last = (MODE == 2 && l == 3);
;     f32x4 pa[4], pb[4], pc[4];
;     {
;         const float* ad = p.ada + ((size_t)l * 17 + r) * 6 * D;
;         int ln, so; const float* pre;
;         if (MODE == 0) { ln = 0; so = 0; pre = p.mix_pre_g; }
;         else if (MODE == 1) { ln = l; so = 3; pre = p.ffn_pre_g + l * D; }
;         else { ln = (l < 3) ? l + 1 : l; so = 0; pre = p.mix_pre_g + ((l < 3) ? l + 1 : l) * D; }
;         const float* ad2 = p.ada + ((size_t)ln * 17 + r) * 6 * D + so * D;
;         const float* gate = ad + (MODE == 1 ? 2 : 5) * D;
;         const float* pg = (MODE == 1 ? p.mix_post_g : p.ffn_post_g) + l * D;
; #pragma unroll
;         for (int i = 0; i < 4; ++i) {
;             const int c = (i * 64 + lane) * 4;
;             if (HASY) pa[i] = *(const f32x4*)(gate + c) * *(const f32x4*)(pg + c);
;             pb[i] = *(const f32x4*)(pre + c) * (*(const f32x4*)(ad2 + D + c) + 1.0f);
;             pc[i] = *(const f32x4*)(ad2 + c);
;         }
;     }
;     auto xptr = [&](int row) -> const float* { return row < NLAT ? p.x + (size_t)row * D : p.ctx + (size_t)(row - NLAT) * D; };
;     RowBuf cur, nxt;
;     rowop_load<HASY, FROM_IN>(cur, xptr(row0), p.xres + (size_t)row0 * D, p.Y + (size_t)row0 * D, lane);
.LBB0_129:
	global_load_dwordx4 v[152:155], v[20:21], off
	global_load_dwordx4 v[156:159], v[22:23], off
	v_lshlrev_b32_e32 v88, 1, v120
	v_add_u32_e32 v50, 0x10000, v88
	v_ashrrev_i32_e32 v51, 31, v50
	s_mov_b32 s22, 0
	s_mov_b64 s[40:41], -1
	s_mov_b64 s[38:39], 0
	global_load_dwordx4 v[160:163], v[24:25], off
	global_load_dwordx4 v[164:167], v[26:27], off
	global_load_dwordx4 v[172:175], v[28:29], off
	global_load_dwordx4 v[176:179], v[30:31], off
	global_load_dwordx4 v[180:183], v[22:23], off offset:1024
	global_load_dwordx4 v[184:187], v[24:25], off offset:1024
	global_load_dwordx4 v[188:191], v[32:33], off
	global_load_dwordx4 v[192:195], v[34:35], off
	global_load_dwordx4 v[208:211], v[36:37], off
	global_load_dwordx4 v[212:215], v[22:23], off offset:2048
	global_load_dwordx4 v[216:219], v[24:25], off offset:2048
	global_load_dwordx4 v[220:223], v[38:39], off
	global_load_dwordx4 v[224:227], v[40:41], off
	global_load_dwordx4 v[228:231], v[18:19], off
	global_load_dwordx4 v[232:235], v[22:23], off offset:3072
	global_load_dwordx4 v[236:239], v[24:25], off offset:3072
	global_load_dwordx4 v[240:243], v[42:43], off
	global_load_dwordx4 v[244:247], v[44:45], off
	s_waitcnt vmcnt(0)
	v_pk_mul_f32 v[52:53], v[154:155], v[158:159]
	v_pk_mul_f32 v[54:55], v[152:153], v[156:157]
	v_pk_add_f32 v[6:7], v[166:167], 1.0 op_sel_hi:[1,0]
	v_pk_add_f32 v[4:5], v[164:165], 1.0 op_sel_hi:[1,0]
	v_pk_mul_f32 v[56:57], v[162:163], v[6:7]
	v_pk_mul_f32 v[58:59], v[160:161], v[4:5]
	v_pk_mul_f32 v[60:61], v[178:179], v[182:183]
	v_pk_mul_f32 v[62:63], v[176:177], v[180:181]
	v_pk_add_f32 v[10:11], v[190:191], 1.0 op_sel_hi:[1,0]
	v_pk_add_f32 v[8:9], v[188:189], 1.0 op_sel_hi:[1,0]
	v_pk_mul_f32 v[64:65], v[186:187], v[10:11]
	v_pk_mul_f32 v[66:67], v[184:185], v[8:9]
	v_pk_mul_f32 v[68:69], v[210:211], v[214:215]
	v_pk_mul_f32 v[70:71], v[208:209], v[212:213]
	v_pk_add_f32 v[14:15], v[222:223], 1.0 op_sel_hi:[1,0]
	v_pk_add_f32 v[12:13], v[220:221], 1.0 op_sel_hi:[1,0]
	v_pk_mul_f32 v[72:73], v[218:219], v[14:15]
	v_pk_mul_f32 v[74:75], v[216:217], v[12:13]
	v_pk_mul_f32 v[76:77], v[230:231], v[234:235]
	v_pk_mul_f32 v[78:79], v[228:229], v[232:233]
	v_pk_add_f32 v[82:83], v[242:243], 1.0 op_sel_hi:[1,0]
	v_pk_add_f32 v[84:85], v[240:241], 1.0 op_sel_hi:[1,0]
	v_pk_mul_f32 v[80:81], v[238:239], v[82:83]
	v_pk_mul_f32 v[82:83], v[236:237], v[84:85]
	v_lshlrev_b64 v[84:85], 11, v[50:51]
	v_lshl_add_u64 v[86:87], v[46:47], 0, v[84:85]
	v_lshl_add_u64 v[84:85], v[48:49], 0, v[84:85]
	v_mov_b64_e32 v[0:1], v[172:173]
	v_mov_b64_e32 v[2:3], v[174:175]
	v_mov_b64_e32 v[4:5], v[192:193]
	v_mov_b64_e32 v[6:7], v[194:195]
	v_mov_b64_e32 v[8:9], v[224:225]
	v_mov_b64_e32 v[10:11], v[226:227]
	v_mov_b64_e32 v[12:13], v[244:245]
	v_mov_b64_e32 v[14:15], v[246:247]
	global_load_dwordx2 v[110:111], v[86:87], off nt
	global_load_dwordx2 v[108:109], v[86:87], off offset:512 nt
	global_load_dwordx2 v[106:107], v[86:87], off offset:1024 nt
	global_load_dwordx2 v[104:105], v[86:87], off offset:1536 nt
	global_load_dwordx2 v[118:119], v[84:85], off nt
	global_load_dwordx2 v[116:117], v[84:85], off offset:512 nt
	global_load_dwordx2 v[112:113], v[84:85], off offset:1024 nt
	global_load_dwordx2 v[114:115], v[84:85], off offset:1536 nt
	v_add_u32_e32 v84, 0x10001, v88
	v_ashrrev_i32_e32 v85, 31, v84
	v_lshlrev_b64 v[86:87], 11, v[84:85]
	v_lshl_add_u64 v[84:85], v[46:47], 0, v[86:87]
	v_lshl_add_u64 v[86:87], v[48:49], 0, v[86:87]
	s_waitcnt vmcnt(0)
	s_branch .LBB0_131

; template <int MODE, bool FROM_IN>
; DI void rowop_run(const Params& p, int l, int row0, int nrows_run, int r, int lane, bool dry = false) {
;     constexpr bool HASY = MODE != 0;
;     const bool last = (MODE == 2 && l == 3);
;     f32x4 pa[4], pb[4], pc[4];
;     {
;         const float* ad = p.ada + ((size_t)l * 17 + r) * 6 * D;
;         int ln, so; const float* pre;
;         if (MODE == 0) { ln = 0; so = 0; pre = p.mix_pre_g; }
;         else if (MODE == 1) { ln = l; so = 3; pre = p.ffn_pre_g + l * D; }
;         else { ln = (l < 3) ? l + 1 : l; so = 0; pre = p.mix_pre_g + ((l < 3) ? l + 1 : l) * D; }
;         const float* ad2 = p.ada + ((size_t)ln * 17 + r) * 6 * D + so * D;
;         const float* gate = ad + (MODE == 1 ? 2 : 5) * D;
;         const float* pg = (MODE == 1 ? p.mix_post_g : p.ffn_post_g) + l * D;
; #pragma unroll
;         for (int i = 0; i < 4; ++i) {
;             const int c = (i * 64 + lane) * 4;
;             if (HASY) pa[i] = *(const f32x4*)(gate + c) * *(const f32x4*)(pg + c);
;             pb[i] = *(const f32x4*)(pre + c) * (*(const f32x4*)(ad2 + D + c) + 1.0f);
;             pc[i] = *(const f32x4*)(ad2 + c);
;         }
;     }
;     auto xptr = [&](int row) -> const float* { return row < NLAT ? p.x + (size_t)row * D : p.ctx + (size_t)(row - NLAT) * D; };
;     RowBuf cur, nxt;
;     rowop_load<HASY, FROM_IN>(cur, xptr(row0), p.xres + (size_t)row0 * D, p.Y + (size_t)row0 * D, lane);
.LBB0_299:
	v_ashrrev_i32_e32 v51, 31, v50
	v_lshlrev_b64 v[0:1], 12, v[50:51]
	v_ashrrev_i32_e32 v53, 31, v52
	v_lshl_add_u64 v[82:83], v[48:49], 0, v[0:1]
	v_lshlrev_b64 v[0:1], 11, v[52:53]
	v_lshl_add_u64 v[84:85], v[42:43], 0, v[0:1]
	v_lshl_add_u64 v[88:89], v[40:41], 0, v[0:1]
	v_ashrrev_i32_e32 v0, 7, v33
	v_readlane_b32 s26, v254, 28
	v_lshlrev_b64 v[2:3], 11, v[50:51]
	v_ashrrev_i32_e32 v1, 31, v0
	v_readlane_b32 s27, v254, 29
	v_lshl_add_u64 v[86:87], v[46:47], 0, v[2:3]
	v_lshl_add_u64 v[90:91], v[40:41], 0, v[2:3]
	v_lshl_add_u64 v[2:3], s[26:27], 0, v[0:1]
	v_mov_b64_e32 v[4:5], s[84:85]
	v_lshl_add_u64 v[0:1], s[42:43], 0, v[0:1]
	v_mad_u64_u32 v[6:7], s[26:27], v2, s3, v[4:5]
	v_mad_u64_u32 v[8:9], s[26:27], v0, s3, v[4:5]
	v_mov_b32_e32 v2, v7
	v_mov_b32_e32 v0, v9
	v_mad_u64_u32 v[2:3], s[26:27], v3, s3, v[2:3]
	v_mad_u64_u32 v[0:1], s[26:27], v1, s3, v[0:1]
	v_mov_b32_e32 v7, v2
	s_mov_b64 s[26:27], 0x5000
	v_lshl_add_u64 v[16:17], v[6:7], 0, s[26:27]
	v_mov_b32_e32 v9, v0
	v_lshl_add_u64 v[0:1], v[16:17], 0, v[128:129]
	global_load_dwordx4 v[152:155], v[0:1], off
	global_load_dwordx4 v[156:159], v[36:37], off
	v_lshl_add_u64 v[20:21], v[8:9], 0, s[20:21]
	v_mov_b32_e32 v55, v129
	v_lshl_add_u64 v[22:23], v[8:9], 0, v[128:129]
	v_mov_b32_e32 v57, v129
	v_mov_b32_e32 v59, v129
	v_lshlrev_b32_e32 v80, 5, v33
	v_ashrrev_i32_e32 v81, 31, v80
	s_mov_b64 s[46:47], 0
	v_lshl_add_u64 v[4:5], v[20:21], 0, v[128:129]
	global_load_dwordx4 v[160:163], v[4:5], off
	global_load_dwordx4 v[164:167], v[38:39], off
	v_lshl_add_u64 v[4:5], v[16:17], 0, v[54:55]
	global_load_dwordx4 v[172:175], v[22:23], off
	global_load_dwordx4 v[176:179], v[4:5], off
	global_load_dwordx4 v[180:183], v[36:37], off offset:1024
	v_lshl_add_u64 v[8:9], v[20:21], 0, v[54:55]
	global_load_dwordx4 v[184:187], v[8:9], off
	global_load_dwordx4 v[188:191], v[38:39], off offset:1024
	v_lshl_add_u64 v[8:9], v[16:17], 0, v[56:57]
	global_load_dwordx4 v[192:195], v[22:23], off offset:1024
	global_load_dwordx4 v[208:211], v[8:9], off
	global_load_dwordx4 v[212:215], v[36:37], off offset:2048
	v_lshl_add_u64 v[12:13], v[20:21], 0, v[56:57]
	global_load_dwordx4 v[216:219], v[12:13], off
	global_load_dwordx4 v[220:223], v[38:39], off offset:2048
	v_lshl_add_u64 v[12:13], v[16:17], 0, v[58:59]
	global_load_dwordx4 v[224:227], v[22:23], off offset:2048
	global_load_dwordx4 v[228:231], v[12:13], off
	global_load_dwordx4 v[232:235], v[36:37], off offset:3072
	v_lshl_add_u64 v[16:17], v[20:21], 0, v[58:59]
	global_load_dwordx4 v[236:239], v[16:17], off
	global_load_dwordx4 v[240:243], v[38:39], off offset:3072
	global_load_dwordx4 v[244:247], v[22:23], off offset:3072
	s_waitcnt vmcnt(0)
	v_pk_mul_f32 v[76:77], v[152:153], v[156:157]
	v_pk_mul_f32 v[78:79], v[154:155], v[158:159]
	v_pk_add_f32 v[4:5], v[160:161], 1.0 op_sel_hi:[1,0]
	v_pk_add_f32 v[6:7], v[162:163], 1.0 op_sel_hi:[1,0]
	v_pk_mul_f32 v[60:61], v[164:165], v[4:5]
	v_pk_mul_f32 v[62:63], v[166:167], v[6:7]
	v_pk_mul_f32 v[92:93], v[176:177], v[180:181]
	v_pk_mul_f32 v[94:95], v[178:179], v[182:183]
	v_pk_add_f32 v[8:9], v[184:185], 1.0 op_sel_hi:[1,0]
	v_pk_add_f32 v[10:11], v[186:187], 1.0 op_sel_hi:[1,0]
	v_pk_mul_f32 v[64:65], v[188:189], v[8:9]
	v_pk_mul_f32 v[66:67], v[190:191], v[10:11]
	v_pk_mul_f32 v[96:97], v[208:209], v[212:213]
	v_pk_mul_f32 v[98:99], v[210:211], v[214:215]
	v_pk_add_f32 v[12:13], v[216:217], 1.0 op_sel_hi:[1,0]
	v_pk_add_f32 v[14:15], v[218:219], 1.0 op_sel_hi:[1,0]
	v_pk_mul_f32 v[68:69], v[220:221], v[12:13]
	v_pk_mul_f32 v[70:71], v[222:223], v[14:15]
	v_pk_mul_f32 v[100:101], v[228:229], v[232:233]
	v_pk_mul_f32 v[102:103], v[230:231], v[234:235]
	v_pk_add_f32 v[16:17], v[236:237], 1.0 op_sel_hi:[1,0]
	v_pk_add_f32 v[18:19], v[238:239], 1.0 op_sel_hi:[1,0]
	v_pk_mul_f32 v[72:73], v[240:241], v[16:17]
	v_lshlrev_b64 v[16:17], 11, v[80:81]
	v_pk_mul_f32 v[74:75], v[242:243], v[18:19]
	v_lshl_add_u64 v[18:19], v[40:41], 0, v[16:17]
	v_lshl_add_u64 v[16:17], v[42:43], 0, v[16:17]
	v_mov_b64_e32 v[0:1], v[172:173]
	v_mov_b64_e32 v[2:3], v[174:175]
	v_mov_b64_e32 v[4:5], v[192:193]
	v_mov_b64_e32 v[6:7], v[194:195]
	v_mov_b64_e32 v[8:9], v[224:225]
	v_mov_b64_e32 v[10:11], v[226:227]
	v_mov_b64_e32 v[12:13], v[244:245]
	v_mov_b64_e32 v[14:15], v[246:247]
	global_load_dwordx2 v[110:111], v[18:19], off nt
	global_load_dwordx2 v[108:109], v[18:19], off offset:512 nt
	global_load_dwordx2 v[106:107], v[18:19], off offset:1024 nt
	global_load_dwordx2 v[104:105], v[18:19], off offset:1536 nt
	global_load_dwordx2 v[116:117], v[16:17], off nt
	global_load_dwordx2 v[114:115], v[16:17], off offset:512 nt
	global_load_dwordx2 v[112:113], v[16:17], off offset:1024 nt
	s_nop 0
	global_load_dwordx2 v[16:17], v[16:17], off offset:1536 nt

; template <int MODE, bool FROM_IN>
; DI void rowop_run(const Params& p, int l, int row0, int nrows_run, int r, int lane, bool dry = false) {
;     constexpr bool HASY = MODE != 0;
;     const bool last = (MODE == 2 && l == 3);
;     f32x4 pa[4], pb[4], pc[4];
;     {
;         const float* ad = p.ada + ((size_t)l * 17 + r) * 6 * D;
;         int ln, so; const float* pre;
;         if (MODE == 0) { ln = 0; so = 0; pre = p.mix_pre_g; }
;         else if (MODE == 1) { ln = l; so = 3; pre = p.ffn_pre_g + l * D; }
;         else { ln = (l < 3) ? l + 1 : l; so = 0; pre = p.mix_pre_g + ((l < 3) ? l + 1 : l) * D; }
;         const float* ad2 = p.ada + ((size_t)ln * 17 + r) * 6 * D + so * D;
;         const float* gate = ad + (MODE == 1 ? 2 : 5) * D;
;         const float* pg = (MODE == 1 ? p.mix_post_g : p.ffn_post_g) + l * D;
; #pragma unroll
;         for (int i = 0; i < 4; ++i) {
;             const int c = (i * 64 + lane) * 4;
;             if (HASY) pa[i] = *(const f32x4*)(gate + c) * *(const f32x4*)(pg + c);
;             pb[i] = *(const f32x4*)(pre + c) * (*(const f32x4*)(ad2 + D + c) + 1.0f);
;             pc[i] = *(const f32x4*)(ad2 + c);
;         }
;     }
;     auto xptr = [&](int row) -> const float* { return row < NLAT ? p.x + (size_t)row * D : p.ctx + (size_t)(row - NLAT) * D; };
;     RowBuf cur, nxt;
;     rowop_load<HASY, FROM_IN>(cur, xptr(row0), p.xres + (size_t)row0 * D, p.Y + (size_t)row0 * D, lane);
.LBB0_318:
	global_load_dwordx4 v[152:155], v[16:17], off
	global_load_dwordx4 v[156:159], v[18:19], off
	v_lshlrev_b32_e32 v88, 1, v120
	v_add_u32_e32 v50, 0x10000, v88
	v_ashrrev_i32_e32 v51, 31, v50
	s_mov_b32 s22, 0
	s_mov_b64 s[38:39], -1
	s_mov_b64 s[34:35], 0
	global_load_dwordx4 v[160:163], v[20:21], off
	global_load_dwordx4 v[164:167], v[22:23], off
	global_load_dwordx4 v[172:175], v[24:25], off
	global_load_dwordx4 v[176:179], v[26:27], off
	global_load_dwordx4 v[180:183], v[18:19], off offset:1024
	global_load_dwordx4 v[184:187], v[20:21], off offset:1024
	global_load_dwordx4 v[188:191], v[28:29], off
	global_load_dwordx4 v[192:195], v[30:31], off
	global_load_dwordx4 v[208:211], v[36:37], off
	global_load_dwordx4 v[212:215], v[18:19], off offset:2048
	global_load_dwordx4 v[216:219], v[20:21], off offset:2048
	global_load_dwordx4 v[220:223], v[38:39], off
	global_load_dwordx4 v[224:227], v[40:41], off
	global_load_dwordx4 v[228:231], v[34:35], off
	global_load_dwordx4 v[232:235], v[18:19], off offset:3072
	global_load_dwordx4 v[236:239], v[20:21], off offset:3072
	global_load_dwordx4 v[240:243], v[42:43], off
	global_load_dwordx4 v[244:247], v[44:45], off
	s_waitcnt vmcnt(0)
	v_pk_mul_f32 v[52:53], v[154:155], v[158:159]
	v_pk_mul_f32 v[54:55], v[152:153], v[156:157]
	v_pk_add_f32 v[6:7], v[166:167], 1.0 op_sel_hi:[1,0]
	v_pk_add_f32 v[4:5], v[164:165], 1.0 op_sel_hi:[1,0]
	v_pk_mul_f32 v[56:57], v[162:163], v[6:7]
	v_pk_mul_f32 v[58:59], v[160:161], v[4:5]
	v_pk_mul_f32 v[60:61], v[178:179], v[182:183]
	v_pk_mul_f32 v[62:63], v[176:177], v[180:181]
	v_pk_add_f32 v[10:11], v[190:191], 1.0 op_sel_hi:[1,0]
	v_pk_add_f32 v[8:9], v[188:189], 1.0 op_sel_hi:[1,0]
	v_pk_mul_f32 v[64:65], v[186:187], v[10:11]
	v_pk_mul_f32 v[66:67], v[184:185], v[8:9]
	v_pk_mul_f32 v[68:69], v[210:211], v[214:215]
	v_pk_mul_f32 v[70:71], v[208:209], v[212:213]
	v_pk_add_f32 v[14:15], v[222:223], 1.0 op_sel_hi:[1,0]
	v_pk_add_f32 v[12:13], v[220:221], 1.0 op_sel_hi:[1,0]
	v_pk_mul_f32 v[72:73], v[218:219], v[14:15]
	v_pk_mul_f32 v[74:75], v[216:217], v[12:13]
	v_pk_mul_f32 v[76:77], v[230:231], v[234:235]
	v_pk_mul_f32 v[78:79], v[228:229], v[232:233]
	v_pk_add_f32 v[82:83], v[242:243], 1.0 op_sel_hi:[1,0]
	v_pk_add_f32 v[84:85], v[240:241], 1.0 op_sel_hi:[1,0]
	v_pk_mul_f32 v[80:81], v[238:239], v[82:83]
	v_pk_mul_f32 v[82:83], v[236:237], v[84:85]
	v_lshlrev_b64 v[84:85], 11, v[50:51]
	v_lshl_add_u64 v[86:87], v[46:47], 0, v[84:85]
	v_lshl_add_u64 v[84:85], v[48:49], 0, v[84:85]
	v_mov_b64_e32 v[0:1], v[172:173]
	v_mov_b64_e32 v[2:3], v[174:175]
	v_mov_b64_e32 v[4:5], v[192:193]
	v_mov_b64_e32 v[6:7], v[194:195]
	v_mov_b64_e32 v[8:9], v[224:225]
	v_mov_b64_e32 v[10:11], v[226:227]
	v_mov_b64_e32 v[12:13], v[244:245]
	v_mov_b64_e32 v[14:15], v[246:247]
	global_load_dwordx2 v[110:111], v[86:87], off nt
	global_load_dwordx2 v[108:109], v[86:87], off offset:512 nt
	global_load_dwordx2 v[106:107], v[86:87], off offset:1024 nt
	global_load_dwordx2 v[104:105], v[86:87], off offset:1536 nt
	global_load_dwordx2 v[118:119], v[84:85], off nt
	global_load_dwordx2 v[116:117], v[84:85], off offset:512 nt
	global_load_dwordx2 v[112:113], v[84:85], off offset:1024 nt
	global_load_dwordx2 v[114:115], v[84:85], off offset:1536 nt
	v_add_u32_e32 v84, 0x10001, v88
	v_ashrrev_i32_e32 v85, 31, v84
	v_lshlrev_b64 v[86:87], 11, v[84:85]
	v_lshl_add_u64 v[84:85], v[46:47], 0, v[86:87]
	v_lshl_add_u64 v[86:87], v[48:49], 0, v[86:87]
	s_waitcnt vmcnt(0)
	s_branch .LBB0_320
